# v3 + NA softmax: validity masks folded into the cached bias registers (32 fewer VALU per item)
# speedup vs baseline: 1.0409x; 1.0019x over previous
.LBB0_716:
	s_add_i32 s10, s91, s83
	s_lshl_b32 s10, s10, 6
	s_and_b32 s26, s10, 0x1c0
	s_or_b32 vcc_hi, s26, s82
	s_lshl_b32 s26, s26, 7
	v_add_u32_e32 v250, s26, v248
	v_add_u32_e32 v251, s26, v249
	s_add_i32 s26, s10, 64
	s_and_b32 s26, s26, 0x1c0
	s_or_b32 s35, s26, s82
	ds_read_b128 v[28:31], v250
	ds_read_b128 v[32:35], v251
	ds_read_b128 v[36:39], v250 offset:512
	ds_read_b128 v[40:43], v251 offset:512
	s_lshl_b32 s26, s26, 7
	v_add_u32_e32 v252, s26, v248
	v_add_u32_e32 v253, s26, v249
	s_add_i32 s26, s10, 0x80
	s_and_b32 s26, s26, 0x1c0
	s_or_b32 vcc_lo, s26, s82
	ds_read_b128 v[44:47], v252
	ds_read_b128 v[164:167], v253
	ds_read_b128 v[168:171], v252 offset:512
	ds_read_b128 v[172:175], v253 offset:512
	s_lshl_b32 s26, s26, 7
	v_add_u32_e32 v250, s26, v248
	v_add_u32_e32 v251, s26, v249
	s_addk_i32 s10, 0xc0
	s_and_b32 s10, s10, 0x1c0
	ds_read_b128 v[176:179], v250
	ds_read_b128 v[180:183], v251
	ds_read_b128 v[200:203], v250 offset:512
	ds_read_b128 v[204:207], v251 offset:512
	s_lshl_b32 s26, s10, 7
	s_or_b32 s10, s10, s82
	v_add_u32_e32 v252, s26, v248
	v_add_u32_e32 v253, s26, v249
	ds_read_b128 v[208:211], v252
	ds_read_b128 v[212:215], v253
	ds_read_b128 v[216:219], v252 offset:512
	ds_read_b128 v[220:223], v253 offset:512
	s_setprio 1
	s_waitcnt lgkmcnt(14)
	v_mfma_f32_16x16x32_bf16 v[28:31], v[28:31], v[24:27], 0
	v_mfma_f32_16x16x32_bf16 v[52:55], v[32:35], v[20:23], v[28:31]
	s_waitcnt lgkmcnt(13)
	v_mfma_f32_16x16x32_bf16 v[28:31], v[36:39], v[24:27], 0
	s_waitcnt lgkmcnt(12)
	v_mfma_f32_16x16x32_bf16 v[48:51], v[40:43], v[20:23], v[28:31]
	s_waitcnt lgkmcnt(11)
	v_mfma_f32_16x16x32_bf16 v[28:31], v[44:47], v[24:27], 0
	s_waitcnt lgkmcnt(10)
	v_mfma_f32_16x16x32_bf16 v[44:47], v[164:167], v[20:23], v[28:31]
	s_waitcnt lgkmcnt(9)
	v_mfma_f32_16x16x32_bf16 v[28:31], v[168:171], v[24:27], 0
	s_waitcnt lgkmcnt(8)
	v_mfma_f32_16x16x32_bf16 v[40:43], v[172:175], v[20:23], v[28:31]
	s_waitcnt lgkmcnt(7)
	v_mfma_f32_16x16x32_bf16 v[28:31], v[176:179], v[24:27], 0
	s_waitcnt lgkmcnt(6)
	v_mfma_f32_16x16x32_bf16 v[36:39], v[180:183], v[20:23], v[28:31]
	s_waitcnt lgkmcnt(5)
	v_mfma_f32_16x16x32_bf16 v[28:31], v[200:203], v[24:27], 0
	s_waitcnt lgkmcnt(4)
	v_mfma_f32_16x16x32_bf16 v[32:35], v[204:207], v[20:23], v[28:31]
	s_waitcnt lgkmcnt(3)
	v_mfma_f32_16x16x32_bf16 v[28:31], v[208:211], v[24:27], 0
	s_waitcnt lgkmcnt(1)
	v_mfma_f32_16x16x32_bf16 v[24:27], v[216:219], v[24:27], 0
	v_mfma_f32_16x16x32_bf16 v[28:31], v[212:215], v[20:23], v[28:31]
	s_waitcnt lgkmcnt(0)
	v_mfma_f32_16x16x32_bf16 v[20:23], v[220:223], v[20:23], v[24:27]
	s_setprio 0
	s_lshl_b32 s26, s90, 6
	s_or_b32 s39, s26, 16
	s_sub_i32 s67, s39, s70
	s_add_i32 s67, s67, s91
	s_cmp_eq_u32 s67, s38
	s_cbranch_scc1 .LBB0_718
	s_sub_i32 s39, s0, s70
	s_add_i32 s39, s39, s91
	s_mul_i32 s39, s39, 31
	v_sub_u32_e32 v0, s39, v61
	s_mulk_i32 s90, 0x744
	v_add_u32_e32 v24, 0xe8, v0
	s_add_i32 s38, s90, 0
	v_add_u32_e32 v25, v24, v88
	v_add_u32_e32 v26, v24, v121
	v_add_u32_e32 v27, v24, v122
	v_add_u32_e32 v129, v24, v123
	v_add_u32_e32 v130, v24, v120
	v_add_u32_e32 v131, v24, v124
	v_add_u32_e32 v132, v24, v125
	v_add_u32_e32 v24, v24, v126
	s_add_i32 s38, s38, 0x22400
	v_cndmask_b32_e64 v129, 0, v129, s[48:49]
	v_cndmask_b32_e64 v130, 0, v130, s[40:41]
	v_cndmask_b32_e64 v131, 0, v131, s[50:51]
	v_cndmask_b32_e64 v132, 0, v132, s[52:53]
	v_cndmask_b32_e64 v24, 0, v24, s[54:55]
	v_cndmask_b32_e64 v25, 0, v25, s[42:43]
	v_cndmask_b32_e64 v26, 0, v26, s[44:45]
	v_cndmask_b32_e64 v27, 0, v27, s[46:47]
	v_lshl_add_u32 v129, v129, 2, s38
	v_lshl_add_u32 v130, v130, 2, s38
	v_lshl_add_u32 v131, v131, 2, s38
	v_lshl_add_u32 v132, v132, 2, s38
	v_lshl_add_u32 v24, v24, 2, s38
	v_lshl_add_u32 v25, v25, 2, s38
	v_lshl_add_u32 v26, v26, 2, s38
	v_lshl_add_u32 v27, v27, 2, s38
	ds_read_b32 v136, v24
	ds_read_b32 v135, v132
	ds_read_b32 v134, v131
	ds_read_b32 v133, v130
	ds_read_b32 v132, v129
	ds_read_b32 v131, v27
	ds_read_b32 v130, v26
	ds_read_b32 v129, v25
	v_add_u32_e32 v24, 0x107, v0
	v_add_u32_e32 v25, v24, v88
	v_add_u32_e32 v26, v24, v121
	v_add_u32_e32 v27, v24, v122
	v_add_u32_e32 v137, v24, v123
	v_add_u32_e32 v138, v24, v120
	v_add_u32_e32 v139, v24, v124
	v_add_u32_e32 v140, v24, v125
	v_add_u32_e32 v24, v24, v126
	v_cndmask_b32_e64 v137, 0, v137, s[48:49]
	v_cndmask_b32_e64 v138, 0, v138, s[40:41]
	v_cndmask_b32_e64 v139, 0, v139, s[50:51]
	v_cndmask_b32_e64 v140, 0, v140, s[52:53]
	v_cndmask_b32_e64 v24, 0, v24, s[54:55]
	v_cndmask_b32_e64 v25, 0, v25, s[42:43]
	v_cndmask_b32_e64 v26, 0, v26, s[44:45]
	v_cndmask_b32_e64 v27, 0, v27, s[46:47]
	v_lshl_add_u32 v137, v137, 2, s38
	v_lshl_add_u32 v138, v138, 2, s38
	v_lshl_add_u32 v139, v139, 2, s38
	v_lshl_add_u32 v140, v140, 2, s38
	v_lshl_add_u32 v24, v24, 2, s38
	s_waitcnt lgkmcnt(0)
	v_lshl_add_u32 v25, v25, 2, s38
	v_lshl_add_u32 v26, v26, 2, s38
	v_lshl_add_u32 v27, v27, 2, s38
	ds_read_b32 v144, v24
	ds_read_b32 v143, v140
	ds_read_b32 v142, v139
	ds_read_b32 v141, v138
	ds_read_b32 v140, v137
	ds_read_b32 v139, v27
	ds_read_b32 v138, v26
	ds_read_b32 v137, v25
	v_add_u32_e32 v24, 0x126, v0
	v_add_u32_e32 v25, v24, v88
	v_add_u32_e32 v26, v24, v121
	v_add_u32_e32 v27, v24, v122
	v_add_u32_e32 v145, v24, v123
	v_add_u32_e32 v146, v24, v120
	v_add_u32_e32 v147, v24, v124
	v_add_u32_e32 v148, v24, v125
	v_add_u32_e32 v24, v24, v126
	v_cndmask_b32_e64 v145, 0, v145, s[48:49]
	v_cndmask_b32_e64 v146, 0, v146, s[40:41]
	v_cndmask_b32_e64 v147, 0, v147, s[50:51]
	v_cndmask_b32_e64 v148, 0, v148, s[52:53]
	v_cndmask_b32_e64 v24, 0, v24, s[54:55]
	v_cndmask_b32_e64 v25, 0, v25, s[42:43]
	v_cndmask_b32_e64 v26, 0, v26, s[44:45]
	v_cndmask_b32_e64 v27, 0, v27, s[46:47]
	v_lshl_add_u32 v145, v145, 2, s38
	v_lshl_add_u32 v146, v146, 2, s38
	v_lshl_add_u32 v147, v147, 2, s38
	v_lshl_add_u32 v148, v148, 2, s38
	v_lshl_add_u32 v24, v24, 2, s38
	s_waitcnt lgkmcnt(0)
	v_lshl_add_u32 v25, v25, 2, s38
	v_lshl_add_u32 v26, v26, 2, s38
	v_lshl_add_u32 v27, v27, 2, s38
	ds_read_b32 v155, v24
	ds_read_b32 v154, v148
	ds_read_b32 v152, v147
	ds_read_b32 v149, v146
	ds_read_b32 v148, v145
	ds_read_b32 v147, v27
	ds_read_b32 v146, v26
	ds_read_b32 v145, v25
	v_add_u32_e32 v0, 0x145, v0
	v_add_u32_e32 v24, v0, v88
	v_add_u32_e32 v25, v0, v121
	v_add_u32_e32 v26, v0, v122
	v_add_u32_e32 v27, v0, v123
	v_add_u32_e32 v156, v0, v120
	v_add_u32_e32 v157, v0, v124
	v_add_u32_e32 v158, v0, v125
	v_add_u32_e32 v0, v0, v126
	v_cndmask_b32_e64 v156, 0, v156, s[40:41]
	v_cndmask_b32_e64 v157, 0, v157, s[50:51]
	v_cndmask_b32_e64 v158, 0, v158, s[52:53]
	v_cndmask_b32_e64 v0, 0, v0, s[54:55]
	v_cndmask_b32_e64 v24, 0, v24, s[42:43]
	v_cndmask_b32_e64 v25, 0, v25, s[44:45]
	v_cndmask_b32_e64 v26, 0, v26, s[46:47]
	v_cndmask_b32_e64 v27, 0, v27, s[48:49]
	v_lshl_add_u32 v156, v156, 2, s38
	v_lshl_add_u32 v157, v157, 2, s38
	v_lshl_add_u32 v158, v158, 2, s38
	v_lshl_add_u32 v0, v0, 2, s38
	s_waitcnt lgkmcnt(0)
	v_lshl_add_u32 v24, v24, 2, s38
	v_lshl_add_u32 v25, v25, 2, s38
	v_lshl_add_u32 v26, v26, 2, s38
	v_lshl_add_u32 v27, v27, 2, s38
	ds_read_b32 v163, v0
	ds_read_b32 v162, v158
	ds_read_b32 v161, v157
	ds_read_b32 v160, v156
	ds_read_b32 v159, v27
	ds_read_b32 v158, v26
	ds_read_b32 v157, v25
	ds_read_b32 v156, v24
	s_mov_b32 s38, s67
	s_waitcnt lgkmcnt(0)
	v_cndmask_b32_e64 v129, v238, v129, s[42:43]
	v_cndmask_b32_e64 v130, v238, v130, s[44:45]
	v_cndmask_b32_e64 v131, v238, v131, s[46:47]
	v_cndmask_b32_e64 v132, v238, v132, s[48:49]
	v_cndmask_b32_e64 v133, v238, v133, s[40:41]
	v_cndmask_b32_e64 v134, v238, v134, s[50:51]
	v_cndmask_b32_e64 v135, v238, v135, s[52:53]
	v_cndmask_b32_e64 v136, v238, v136, s[54:55]
	v_cndmask_b32_e64 v137, v238, v137, s[42:43]
	v_cndmask_b32_e64 v138, v238, v138, s[44:45]
	v_cndmask_b32_e64 v139, v238, v139, s[46:47]
	v_cndmask_b32_e64 v140, v238, v140, s[48:49]
	v_cndmask_b32_e64 v141, v238, v141, s[40:41]
	v_cndmask_b32_e64 v142, v238, v142, s[50:51]
	v_cndmask_b32_e64 v143, v238, v143, s[52:53]
	v_cndmask_b32_e64 v144, v238, v144, s[54:55]
	v_cndmask_b32_e64 v145, v238, v145, s[42:43]
	v_cndmask_b32_e64 v146, v238, v146, s[44:45]
	v_cndmask_b32_e64 v147, v238, v147, s[46:47]
	v_cndmask_b32_e64 v148, v238, v148, s[48:49]
	v_cndmask_b32_e64 v149, v238, v149, s[40:41]
	v_cndmask_b32_e64 v152, v238, v152, s[50:51]
	v_cndmask_b32_e64 v154, v238, v154, s[52:53]
	v_cndmask_b32_e64 v155, v238, v155, s[54:55]
	v_cndmask_b32_e64 v156, v238, v156, s[42:43]
	v_cndmask_b32_e64 v157, v238, v157, s[44:45]
	v_cndmask_b32_e64 v158, v238, v158, s[46:47]
	v_cndmask_b32_e64 v159, v238, v159, s[48:49]
	v_cndmask_b32_e64 v160, v238, v160, s[40:41]
	v_cndmask_b32_e64 v161, v238, v161, s[50:51]
	v_cndmask_b32_e64 v162, v238, v162, s[52:53]
	v_cndmask_b32_e64 v163, v238, v163, s[54:55]
.LBB0_718:
	v_fmamk_f32 v24, v52, 0x3e38aa3b, v129
	v_fmamk_f32 v25, v53, 0x3e38aa3b, v130
	s_mov_b32 s39, 0xff800000
	v_fmamk_f32 v26, v54, 0x3e38aa3b, v131
	v_fmamk_f32 v27, v55, 0x3e38aa3b, v132
	v_max3_f32 v0, v24, s39, v25
	v_fmamk_f32 v48, v48, 0x3e38aa3b, v133
	v_fmamk_f32 v49, v49, 0x3e38aa3b, v134
	v_max3_f32 v0, v0, v26, v27
	v_fmamk_f32 v50, v50, 0x3e38aa3b, v135
	v_fmamk_f32 v51, v51, 0x3e38aa3b, v136
	v_max3_f32 v0, v0, v48, v49
	v_fmamk_f32 v44, v44, 0x3e38aa3b, v137
	v_fmamk_f32 v45, v45, 0x3e38aa3b, v138
	v_max3_f32 v0, v0, v50, v51
	v_fmamk_f32 v46, v46, 0x3e38aa3b, v139
	v_fmamk_f32 v47, v47, 0x3e38aa3b, v140
	v_max3_f32 v0, v0, v44, v45
	v_fmamk_f32 v40, v40, 0x3e38aa3b, v141
	v_fmamk_f32 v41, v41, 0x3e38aa3b, v142
	v_max3_f32 v0, v0, v46, v47
	v_fmamk_f32 v42, v42, 0x3e38aa3b, v143
	v_fmamk_f32 v43, v43, 0x3e38aa3b, v144
	v_max3_f32 v0, v0, v40, v41
	v_fmamk_f32 v36, v36, 0x3e38aa3b, v145
	v_fmamk_f32 v37, v37, 0x3e38aa3b, v146
	v_max3_f32 v0, v0, v42, v43
	v_fmamk_f32 v38, v38, 0x3e38aa3b, v147
	v_fmamk_f32 v39, v39, 0x3e38aa3b, v148
	v_max3_f32 v0, v0, v36, v37
	v_fmamk_f32 v32, v32, 0x3e38aa3b, v149
	v_fmamk_f32 v33, v33, 0x3e38aa3b, v152
	v_max3_f32 v0, v0, v38, v39
	v_fmamk_f32 v34, v34, 0x3e38aa3b, v154
	v_fmamk_f32 v35, v35, 0x3e38aa3b, v155
	v_max3_f32 v0, v0, v32, v33
	v_fmamk_f32 v28, v28, 0x3e38aa3b, v156
	v_fmamk_f32 v29, v29, 0x3e38aa3b, v157
	v_max3_f32 v0, v0, v34, v35
	v_fmamk_f32 v30, v30, 0x3e38aa3b, v158
	v_fmamk_f32 v31, v31, 0x3e38aa3b, v159
	v_max3_f32 v0, v0, v28, v29
	v_fmamk_f32 v20, v20, 0x3e38aa3b, v160
	v_fmamk_f32 v21, v21, 0x3e38aa3b, v161
	v_max3_f32 v0, v0, v30, v31
	v_fmamk_f32 v22, v22, 0x3e38aa3b, v162
	v_fmamk_f32 v23, v23, 0x3e38aa3b, v163
	v_max3_f32 v0, v0, v20, v21
	v_max3_f32 v0, v0, v22, v23
	v_mov_b32_e32 v52, v0
	s_nop 1
	v_permlane16_swap_b32_e32 v0, v52
	v_max_f32_e32 v52, v52, v52
	v_max_f32_e32 v0, v0, v0
	v_max_f32_e32 v0, v0, v52
	v_mov_b32_e32 v52, v0
	s_nop 1
	v_permlane32_swap_b32_e32 v0, v52
	v_max_f32_e32 v52, v52, v52
	v_max_f32_e32 v0, v0, v0
	v_max_f32_e32 v0, v0, v52
	v_sub_f32_e32 v24, v24, v0
	v_exp_f32_e32 v52, v24
	v_sub_f32_e32 v24, v25, v0
	v_exp_f32_e32 v53, v24
	v_sub_f32_e32 v24, v26, v0
	v_exp_f32_e32 v54, v24
	v_sub_f32_e32 v24, v27, v0
	v_exp_f32_e32 v55, v24
	v_sub_f32_e32 v25, v48, v0
	v_add_f32_e32 v24, 0, v52
	v_exp_f32_e32 v164, v25
	v_sub_f32_e32 v25, v49, v0
	v_add_f32_e32 v24, v53, v24
	v_exp_f32_e32 v165, v25
	v_sub_f32_e32 v25, v50, v0
	v_add_f32_e32 v24, v54, v24
	v_exp_f32_e32 v166, v25
	v_sub_f32_e32 v25, v51, v0
	v_add_f32_e32 v24, v55, v24
	v_exp_f32_e32 v167, v25
	v_sub_f32_e32 v25, v44, v0
	v_add_f32_e32 v24, v164, v24
	v_exp_f32_e32 v168, v25
	v_sub_f32_e32 v25, v45, v0
	v_add_f32_e32 v24, v165, v24
	v_exp_f32_e32 v169, v25
	v_sub_f32_e32 v25, v46, v0
	v_add_f32_e32 v24, v166, v24
	v_exp_f32_e32 v170, v25
	v_sub_f32_e32 v25, v47, v0
	v_add_f32_e32 v24, v167, v24
	v_exp_f32_e32 v171, v25
	v_sub_f32_e32 v25, v40, v0
	v_add_f32_e32 v24, v168, v24
	v_exp_f32_e32 v172, v25
	v_sub_f32_e32 v25, v41, v0
	v_add_f32_e32 v24, v169, v24
	v_exp_f32_e32 v173, v25
	v_sub_f32_e32 v25, v42, v0
	v_add_f32_e32 v24, v170, v24
	v_exp_f32_e32 v174, v25
	v_sub_f32_e32 v25, v43, v0
	v_add_f32_e32 v24, v171, v24
	v_exp_f32_e32 v175, v25
	v_sub_f32_e32 v25, v36, v0
	v_add_f32_e32 v24, v172, v24
	v_exp_f32_e32 v176, v25
	v_sub_f32_e32 v25, v37, v0
	v_add_f32_e32 v24, v173, v24
	v_exp_f32_e32 v177, v25
	v_sub_f32_e32 v25, v38, v0
	v_add_f32_e32 v24, v174, v24
	v_exp_f32_e32 v178, v25
	v_sub_f32_e32 v25, v39, v0
	v_add_f32_e32 v24, v175, v24
	v_exp_f32_e32 v179, v25
	v_sub_f32_e32 v25, v32, v0
	v_add_f32_e32 v24, v176, v24
	v_exp_f32_e32 v180, v25
	v_sub_f32_e32 v25, v33, v0
	v_add_f32_e32 v24, v177, v24
	v_exp_f32_e32 v181, v25
	v_sub_f32_e32 v25, v34, v0
	v_add_f32_e32 v24, v178, v24
	v_exp_f32_e32 v182, v25
	v_sub_f32_e32 v25, v35, v0
	v_add_f32_e32 v24, v179, v24
	v_exp_f32_e32 v183, v25
	v_sub_f32_e32 v25, v28, v0
	v_add_f32_e32 v24, v180, v24
	v_exp_f32_e32 v184, v25
	v_sub_f32_e32 v25, v29, v0
	v_add_f32_e32 v24, v181, v24
	v_exp_f32_e32 v185, v25
	v_sub_f32_e32 v25, v30, v0
	v_add_f32_e32 v24, v182, v24
	v_exp_f32_e32 v199, v25
	v_sub_f32_e32 v25, v31, v0
	v_add_f32_e32 v24, v183, v24
	v_exp_f32_e32 v200, v25
	v_sub_f32_e32 v20, v20, v0
	v_add_f32_e32 v24, v184, v24
	v_exp_f32_e32 v201, v20
	v_sub_f32_e32 v20, v21, v0
	v_add_f32_e32 v24, v185, v24
	v_exp_f32_e32 v202, v20
	v_sub_f32_e32 v20, v22, v0
	v_add_f32_e32 v24, v199, v24
	v_exp_f32_e32 v203, v20
	v_sub_f32_e32 v20, v23, v0
	v_add_f32_e32 v24, v200, v24
	v_exp_f32_e32 v204, v20
	v_add_f32_e32 v20, v201, v24
	v_add_f32_e32 v20, v202, v20
	v_add_f32_e32 v20, v203, v20
	v_lshl_add_u32 v32, vcc_hi, 1, v127
	v_lshl_add_u32 v48, s35, 1, v127
	v_add_f32_e32 v205, v204, v20
	ds_read_b128 v[20:23], v32
	ds_read_b128 v[24:27], v32 offset:16640
	ds_read_b128 v[28:31], v32 offset:33280
	ds_read_b128 v[32:35], v32 offset:49920
	ds_read_b128 v[36:39], v48
	ds_read_b128 v[40:43], v48 offset:16640
	ds_read_b128 v[44:47], v48 offset:33280
	ds_read_b128 v[48:51], v48 offset:49920
	v_mov_b32_e32 v206, v205
	s_nop 1
	v_permlane16_swap_b32_e32 v205, v206
	v_add_f32_e32 v205, v205, v206
	v_mov_b32_e32 v206, v205
	s_nop 1
	v_permlane32_swap_b32_e32 v205, v206
	v_cvt_pk_bf16_f32 v52, v52, v53
	v_cvt_pk_bf16_f32 v53, v54, v55
	v_cvt_pk_bf16_f32 v54, v164, v165
	v_cvt_pk_bf16_f32 v55, v166, v167
	s_setprio 1
	s_waitcnt lgkmcnt(7)
	v_mfma_f32_16x16x32_bf16 v[20:23], v[20:23], v[52:55], 0
	s_setprio 0
	s_setprio 1
	s_waitcnt lgkmcnt(6)
	v_mfma_f32_16x16x32_bf16 v[24:27], v[24:27], v[52:55], 0
	s_setprio 0
	s_setprio 1
	s_waitcnt lgkmcnt(5)
	v_mfma_f32_16x16x32_bf16 v[28:31], v[28:31], v[52:55], 0
	s_setprio 0
	s_setprio 1
	s_waitcnt lgkmcnt(4)
	v_mfma_f32_16x16x32_bf16 v[32:35], v[32:35], v[52:55], 0
	s_setprio 0
	v_cvt_pk_bf16_f32 v52, v168, v169
	v_cvt_pk_bf16_f32 v53, v170, v171
	v_cvt_pk_bf16_f32 v54, v172, v173
	v_cvt_pk_bf16_f32 v55, v174, v175
	s_setprio 1
	s_waitcnt lgkmcnt(3)
	v_mfma_f32_16x16x32_bf16 v[20:23], v[36:39], v[52:55], v[20:23]
	s_setprio 0
	s_setprio 1
	s_waitcnt lgkmcnt(2)
	v_mfma_f32_16x16x32_bf16 v[24:27], v[40:43], v[52:55], v[24:27]
	s_setprio 0
	s_setprio 1
	s_waitcnt lgkmcnt(1)
	v_mfma_f32_16x16x32_bf16 v[28:31], v[44:47], v[52:55], v[28:31]
	s_setprio 0
	s_setprio 1
	s_waitcnt lgkmcnt(0)
	v_mfma_f32_16x16x32_bf16 v[32:35], v[48:51], v[52:55], v[32:35]
	s_setprio 0
	v_lshl_add_u32 v48, vcc_lo, 1, v127
	v_lshl_add_u32 v172, s10, 1, v127
	ds_read_b128 v[36:39], v48
	ds_read_b128 v[40:43], v48 offset:16640
	ds_read_b128 v[44:47], v48 offset:33280
	ds_read_b128 v[48:51], v48 offset:49920
	ds_read_b128 v[52:55], v172
	ds_read_b128 v[164:167], v172 offset:16640
	ds_read_b128 v[168:171], v172 offset:33280
	ds_read_b128 v[172:175], v172 offset:49920
	v_cvt_pk_bf16_f32 v176, v176, v177
	v_cvt_pk_bf16_f32 v177, v178, v179
	v_cvt_pk_bf16_f32 v178, v180, v181
	v_cvt_pk_bf16_f32 v179, v182, v183
	s_setprio 1
	s_waitcnt lgkmcnt(7)
	v_mfma_f32_16x16x32_bf16 v[20:23], v[36:39], v[176:179], v[20:23]
	s_setprio 0
	s_setprio 1
	s_waitcnt lgkmcnt(6)
	v_mfma_f32_16x16x32_bf16 v[24:27], v[40:43], v[176:179], v[24:27]
	s_setprio 0
	s_setprio 1
	s_waitcnt lgkmcnt(5)
	v_mfma_f32_16x16x32_bf16 v[36:39], v[44:47], v[176:179], v[28:31]
	s_setprio 0
	s_setprio 1
	s_waitcnt lgkmcnt(4)
	v_mfma_f32_16x16x32_bf16 v[40:43], v[48:51], v[176:179], v[32:35]
	s_setprio 0
	v_cvt_pk_bf16_f32 v44, v184, v185
	v_cvt_pk_bf16_f32 v45, v199, v200
	v_cvt_pk_bf16_f32 v46, v201, v202
	v_cvt_pk_bf16_f32 v47, v203, v204
	s_setprio 1
	s_waitcnt lgkmcnt(3)
	v_mfma_f32_16x16x32_bf16 v[32:35], v[52:55], v[44:47], v[20:23]
	s_setprio 0
	s_setprio 1
	s_waitcnt lgkmcnt(2)
	v_mfma_f32_16x16x32_bf16 v[28:31], v[164:167], v[44:47], v[24:27]
	s_setprio 0
	s_setprio 1
	s_waitcnt lgkmcnt(1)
	v_mfma_f32_16x16x32_bf16 v[24:27], v[168:171], v[44:47], v[36:39]
	s_setprio 0
	s_setprio 1
	s_waitcnt lgkmcnt(0)
	v_mfma_f32_16x16x32_bf16 v[20:23], v[172:175], v[44:47], v[40:43]
	s_setprio 0
	s_andn2_b64 vcc, exec, s[80:81]
	v_add_f32_e32 v38, v205, v206
	s_cbranch_vccnz .LBB0_720
	v_cvt_pk_f16_f32 v36, v32, v33
	v_cvt_pk_f16_f32 v37, v34, v35
	ds_write2st64_b32 v128, v36, v37 offset0:2 offset1:3
	v_cvt_pk_f16_f32 v36, v28, v29
	v_cvt_pk_f16_f32 v37, v30, v31
	ds_write2st64_b32 v128, v36, v37 offset0:4 offset1:5
	v_cvt_pk_f16_f32 v36, v24, v25
	v_cvt_pk_f16_f32 v37, v26, v27
	ds_write2st64_b32 v128, v36, v37 offset0:6 offset1:7
	v_cvt_pk_f16_f32 v36, v20, v21
	v_cvt_pk_f16_f32 v37, v22, v23
	ds_write2st64_b32 v128, v0, v38 offset1:1
	ds_write2st64_b32 v128, v36, v37 offset0:8 offset1:9
